# convert_weights: software-pipelined tile conversion, dwordx4 row loads, two register sets
# speedup vs baseline: 1.0099x; 1.0075x over previous
.LBB0_19:
	s_cmp_gt_u32 s0, 12
	s_cselect_b64 s[64:65], -1, 0
	s_cmp_lt_u32 s0, 13
	s_cselect_b64 s[4:5], -1, 0
	v_writelane_b32 v251, s4, 57
	s_waitcnt lgkmcnt(0)
	v_add_co_u32_e64 v0, s[6:7], s0, -1
	v_writelane_b32 v251, s5, 58
	v_writelane_b32 v251, s0, 59
	s_add_i32 s0, s0, -13
	v_readfirstlane_b32 s1, v0
	s_cmp_lt_u32 s1, 12
	s_cselect_b32 s4, s1, s0
	s_and_b64 s[0:1], s[6:7], exec
	s_mov_b32 s0, s4
	v_writelane_b32 v251, s0, 60
	s_nop 1
	v_writelane_b32 v251, s1, 61
	s_cselect_b32 s0, s4, -1
	s_cmp_lg_u32 s0, 11
	v_writelane_b32 v251, s0, 62
	s_cselect_b64 s[0:1], -1, 0
	s_or_b64 s[0:1], s[0:1], s[64:65]
	s_and_b64 s[0:1], s[6:7], s[0:1]
	s_and_b64 vcc, exec, s[0:1]
	s_cbranch_vccnz .LBB0_104
	v_readlane_b32 s4, v252, 2
	v_readlane_b32 s0, v252, 0
	v_readlane_b32 s5, v252, 3
	v_mov_b32_e32 v0, v162
	v_readlane_b32 s1, v252, 1
	s_andn2_b64 vcc, exec, s[4:5]
	s_cbranch_vccnz .LBB0_104
	s_load_dwordx2 s[4:5], s[0:1], 0x158
	s_waitcnt vmcnt(0)
	v_ashrrev_i32_e32 v2, 5, v0
	v_and_b32_e32 v4, 31, v0
	v_ashrrev_i32_e32 v16, 3, v0
	v_lshlrev_b32_e32 v0, 3, v0
	s_waitcnt lgkmcnt(0)
	s_add_u32 s36, s4, 0x100000
	s_addc_u32 s37, s5, 0
	s_and_b64 s[4:5], s[6:7], exec
	s_cselect_b32 s72, 0x10000, 0
	s_mov_b64 s[8:9], s[72:73]
	s_cselect_b32 s72, 0x8000, 0
	s_mov_b64 s[10:11], s[72:73]
	s_cselect_b32 s72, 0x100000, 0
	v_and_b32_e32 v0, 56, v0
	s_mov_b64 s[12:13], s[72:73]
	s_cselect_b32 s72, 0x40000, 0
	v_mul_u32_u24_e32 v3, 0x84, v0
	v_lshlrev_b32_e32 v5, 2, v16
	v_readlane_b32 s5, v252, 7
	s_movk_i32 s4, 0x84
	s_mov_b64 s[14:15], s[72:73]
	s_cselect_b32 s72, 0x2c0000, 0
	v_add3_u32 v17, s5, v3, v5
	v_mul_lo_u32 v5, v2, s4
	v_lshlrev_b32_e32 v6, 2, v4
	s_mov_b64 s[16:17], s[72:73]
	s_cselect_b32 s72, 0x7c0000, 0
	v_add_u32_e32 v19, 8, v16
	v_add_u32_e32 v21, 24, v16
	v_add3_u32 v23, v5, v6, s5
	v_readlane_b32 s4, v251, 49
	s_cselect_b32 s38, 8, 0
	s_cselect_b32 s39, 0x400, 0
	s_cselect_b32 s40, 3, 0
	s_mov_b64 s[18:19], s[72:73]
	v_and_b32_e32 v18, 15, v16
	v_and_b32_e32 v20, 15, v19
	v_and_b32_e32 v22, 15, v21
	v_ashrrev_i32_e32 v3, 31, v2
	v_lshlrev_b32_e32 v4, 2, v4
	v_mov_b32_e32 v5, v1
	v_lshlrev_b32_e32 v0, 1, v0
	s_mov_b32 s41, s4
	v_readlane_b32 s5, v251, 50
	v_readlane_b32 s98, v252, 7
	v_and_b32_e32 v132, 7, v162
	v_lshlrev_b32_e32 v132, 4, v132
	v_mov_b32_e32 v133, 0x84
	v_mad_u32_u24 v132, v16, v133, v132
	v_add_u32_e32 v132, s98, v132
	s_mov_b32 s98, 0
	s_mov_b32 s99, 0
	s_branch .LBB0_23
.LBB0_22:
	v_readlane_b32 s4, v251, 53
	s_nop 3
	s_add_i32 s41, s41, s4
	s_cmpk_lt_i32 s41, 0x27e0
	v_readlane_b32 s5, v251, 54
	s_cbranch_scc0 .Lcw_drain

.LBB0_71:
	s_add_u32 s22, s36, s22
	s_addc_u32 s23, s37, s23
	s_lshl_b64 s[4:5], s[26:27], 1
	s_add_u32 s4, s22, s4
	s_addc_u32 s5, s23, s5
	v_lshl_add_u64 v[8:9], s[4:5], 0, v[0:1]
	v_readfirstlane_b32 s4, v6
	v_readfirstlane_b32 s5, v7
	v_add_u32_e32 v24, s24, v16
	v_add_u32_e32 v25, s24, v19
	v_add_u32_e32 v26, 16, v24
	v_add_u32_e32 v27, s24, v21
	s_and_b64 vcc, exec, s[30:31]
	s_cbranch_vccz .Lcw_rmap0
	v_lshlrev_b32_e32 v24, 1, v24
	v_and_b32_e32 v24, 0xffffffe0, v24
	v_or3_b32 v24, v18, v24, s43
	v_lshlrev_b32_e32 v25, 1, v25
	v_and_b32_e32 v25, 0xffffffe0, v25
	v_or3_b32 v25, v20, v25, s43
	v_lshlrev_b32_e32 v26, 1, v26
	v_and_b32_e32 v26, 0xffffffe0, v26
	v_or3_b32 v26, v18, v26, s43
	v_lshlrev_b32_e32 v27, 1, v27
	v_and_b32_e32 v27, 0xffffffe0, v27
	v_or3_b32 v27, v22, v27, s43
	s_branch .Lcw_addr
.Lcw_rmap0:
	v_add_u32_e32 v24, s44, v24
	v_add_u32_e32 v25, s44, v25
	v_add_u32_e32 v26, s44, v26
	v_add_u32_e32 v27, s44, v27
.Lcw_addr:
	v_mul_lo_u32 v24, v24, s20
	v_mul_lo_u32 v25, v25, s20
	v_mul_lo_u32 v26, v26, s20
	v_mul_lo_u32 v27, v27, s20
	v_mov_b32_e32 v29, 0
	v_add_u32_e32 v10, s26, v16
	v_mul_lo_u32 v10, v10, s42
	v_and_b32_e32 v12, 7, v162
	v_lshl_add_u32 v10, v12, 2, v10
	v_mov_b32_e32 v11, 0
	v_lshl_add_u64 v[10:11], v[10:11], 2, s[4:5]
	s_lshl_b32 s4, s42, 5
	s_mov_b32 s5, 0
	s_cmp_eq_u32 s99, 0
	s_cbranch_scc0 .Lcw_issueB
	v_mov_b32_e32 v28, v24
	v_lshl_add_u64 v[72:73], v[28:29], 1, v[8:9]
	v_mov_b32_e32 v28, v25
	v_lshl_add_u64 v[74:75], v[28:29], 1, v[8:9]
	v_mov_b32_e32 v28, v26
	v_lshl_add_u64 v[76:77], v[28:29], 1, v[8:9]
	v_mov_b32_e32 v28, v27
	v_lshl_add_u64 v[78:79], v[28:29], 1, v[8:9]
	s_and_b64 vcc, exec, s[34:35]
	s_cbranch_vccz .Lcw_nogain_A
	v_add_u32_e32 v30, s26, v16
	v_lshlrev_b32_e32 v30, 2, v30
	v_mov_b32_e32 v31, 0
	v_lshl_add_u64 v[30:31], v[30:31], 0, s[28:29]
	global_load_dword v64, v[30:31], off offset:0
	global_load_dword v65, v[30:31], off offset:32
	global_load_dword v66, v[30:31], off offset:64
	global_load_dword v67, v[30:31], off offset:96
	global_load_dword v68, v[30:31], off offset:128
	global_load_dword v69, v[30:31], off offset:160
	global_load_dword v70, v[30:31], off offset:192
	global_load_dword v71, v[30:31], off offset:224
	s_branch .Lcw_wload_A
.Lcw_nogain_A:
	v_mov_b32_e32 v64, 1.0
	v_mov_b32_e32 v65, 1.0
	v_mov_b32_e32 v66, 1.0
	v_mov_b32_e32 v67, 1.0
	v_mov_b32_e32 v68, 1.0
	v_mov_b32_e32 v69, 1.0
	v_mov_b32_e32 v70, 1.0
	v_mov_b32_e32 v71, 1.0
.Lcw_wload_A:
	global_load_dwordx4 v[32:35], v[10:11], off
	v_lshl_add_u64 v[10:11], v[10:11], 0, s[4:5]
	global_load_dwordx4 v[36:39], v[10:11], off
	v_lshl_add_u64 v[10:11], v[10:11], 0, s[4:5]
	global_load_dwordx4 v[40:43], v[10:11], off
	v_lshl_add_u64 v[10:11], v[10:11], 0, s[4:5]
	global_load_dwordx4 v[44:47], v[10:11], off
	v_lshl_add_u64 v[10:11], v[10:11], 0, s[4:5]
	global_load_dwordx4 v[48:51], v[10:11], off
	v_lshl_add_u64 v[10:11], v[10:11], 0, s[4:5]
	global_load_dwordx4 v[52:55], v[10:11], off
	v_lshl_add_u64 v[10:11], v[10:11], 0, s[4:5]
	global_load_dwordx4 v[56:59], v[10:11], off
	v_lshl_add_u64 v[10:11], v[10:11], 0, s[4:5]
	global_load_dwordx4 v[60:63], v[10:11], off
	s_cmp_eq_u32 s98, 0
	s_cbranch_scc1 .Lcw_A_done
	s_waitcnt vmcnt(8)
	v_mul_f32_e32 v80, v112, v80
	v_mul_f32_e32 v81, v112, v81
	v_mul_f32_e32 v82, v112, v82
	v_mul_f32_e32 v83, v112, v83
	ds_write_b32 v132, v80 offset:0
	ds_write_b32 v132, v81 offset:4
	ds_write_b32 v132, v82 offset:8
	ds_write_b32 v132, v83 offset:12
	v_mul_f32_e32 v84, v113, v84
	v_mul_f32_e32 v85, v113, v85
	v_mul_f32_e32 v86, v113, v86
	v_mul_f32_e32 v87, v113, v87
	ds_write_b32 v132, v84 offset:1056
	ds_write_b32 v132, v85 offset:1060
	ds_write_b32 v132, v86 offset:1064
	ds_write_b32 v132, v87 offset:1068
	v_mul_f32_e32 v88, v114, v88
	v_mul_f32_e32 v89, v114, v89
	v_mul_f32_e32 v90, v114, v90
	v_mul_f32_e32 v91, v114, v91
	ds_write_b32 v132, v88 offset:2112
	ds_write_b32 v132, v89 offset:2116
	ds_write_b32 v132, v90 offset:2120
	ds_write_b32 v132, v91 offset:2124
	v_mul_f32_e32 v92, v115, v92
	v_mul_f32_e32 v93, v115, v93
	v_mul_f32_e32 v94, v115, v94
	v_mul_f32_e32 v95, v115, v95
	ds_write_b32 v132, v92 offset:3168
	ds_write_b32 v132, v93 offset:3172
	ds_write_b32 v132, v94 offset:3176
	ds_write_b32 v132, v95 offset:3180
	v_mul_f32_e32 v96, v116, v96
	v_mul_f32_e32 v97, v116, v97
	v_mul_f32_e32 v98, v116, v98
	v_mul_f32_e32 v99, v116, v99
	ds_write_b32 v132, v96 offset:4224
	ds_write_b32 v132, v97 offset:4228
	ds_write_b32 v132, v98 offset:4232
	ds_write_b32 v132, v99 offset:4236
	v_mul_f32_e32 v100, v117, v100
	v_mul_f32_e32 v101, v117, v101
	v_mul_f32_e32 v102, v117, v102
	v_mul_f32_e32 v103, v117, v103
	ds_write_b32 v132, v100 offset:5280
	ds_write_b32 v132, v101 offset:5284
	ds_write_b32 v132, v102 offset:5288
	ds_write_b32 v132, v103 offset:5292
	v_mul_f32_e32 v104, v118, v104
	v_mul_f32_e32 v105, v118, v105
	v_mul_f32_e32 v106, v118, v106
	v_mul_f32_e32 v107, v118, v107
	ds_write_b32 v132, v104 offset:6336
	ds_write_b32 v132, v105 offset:6340
	ds_write_b32 v132, v106 offset:6344
	ds_write_b32 v132, v107 offset:6348
	v_mul_f32_e32 v108, v119, v108
	v_mul_f32_e32 v109, v119, v109
	v_mul_f32_e32 v110, v119, v110
	v_mul_f32_e32 v111, v119, v111
	ds_write_b32 v132, v108 offset:7392
	ds_write_b32 v132, v109 offset:7396
	ds_write_b32 v132, v110 offset:7400
	ds_write_b32 v132, v111 offset:7404
	s_waitcnt lgkmcnt(0)
	ds_read2_b32 v[80:81], v17 offset0:0 offset1:33
	ds_read2_b32 v[82:83], v17 offset0:66 offset1:99
	ds_read2_b32 v[84:85], v17 offset0:132 offset1:165
	ds_read2_b32 v[86:87], v17 offset0:198 offset1:231
	ds_read2_b32 v[88:89], v17 offset0:8 offset1:41
	ds_read2_b32 v[90:91], v17 offset0:74 offset1:107
	ds_read2_b32 v[92:93], v17 offset0:140 offset1:173
	ds_read2_b32 v[94:95], v17 offset0:206 offset1:239
	ds_read2_b32 v[96:97], v17 offset0:16 offset1:49
	ds_read2_b32 v[98:99], v17 offset0:82 offset1:115
	ds_read2_b32 v[100:101], v17 offset0:148 offset1:181
	ds_read2_b32 v[102:103], v17 offset0:214 offset1:247
	ds_read2_b32 v[104:105], v17 offset0:24 offset1:57
	ds_read2_b32 v[106:107], v17 offset0:90 offset1:123
	ds_read2_b32 v[108:109], v17 offset0:156 offset1:189
	ds_read2_b32 v[110:111], v17 offset0:222 offset1:255
	s_waitcnt lgkmcnt(12)
	v_cvt_pk_bf16_f32 v80, v80, v81
	v_cvt_pk_bf16_f32 v81, v82, v83
	v_cvt_pk_bf16_f32 v82, v84, v85
	v_cvt_pk_bf16_f32 v83, v86, v87
	global_store_dwordx4 v[120:121], v[80:83], off
	s_waitcnt lgkmcnt(8)
	v_cvt_pk_bf16_f32 v88, v88, v89
	v_cvt_pk_bf16_f32 v89, v90, v91
	v_cvt_pk_bf16_f32 v90, v92, v93
	v_cvt_pk_bf16_f32 v91, v94, v95
	global_store_dwordx4 v[122:123], v[88:91], off
	s_waitcnt lgkmcnt(4)
	v_cvt_pk_bf16_f32 v96, v96, v97
	v_cvt_pk_bf16_f32 v97, v98, v99
	v_cvt_pk_bf16_f32 v98, v100, v101
	v_cvt_pk_bf16_f32 v99, v102, v103
	global_store_dwordx4 v[124:125], v[96:99], off
	s_waitcnt lgkmcnt(0)
	v_cvt_pk_bf16_f32 v104, v104, v105
	v_cvt_pk_bf16_f32 v105, v106, v107
	v_cvt_pk_bf16_f32 v106, v108, v109
	v_cvt_pk_bf16_f32 v107, v110, v111
	global_store_dwordx4 v[126:127], v[104:107], off
.Lcw_A_done:
	s_mov_b32 s98, 1
	s_mov_b32 s99, 1
	s_branch .LBB0_22
.Lcw_issueB:
	v_mov_b32_e32 v28, v24
	v_lshl_add_u64 v[120:121], v[28:29], 1, v[8:9]
	v_mov_b32_e32 v28, v25
	v_lshl_add_u64 v[122:123], v[28:29], 1, v[8:9]
	v_mov_b32_e32 v28, v26
	v_lshl_add_u64 v[124:125], v[28:29], 1, v[8:9]
	v_mov_b32_e32 v28, v27
	v_lshl_add_u64 v[126:127], v[28:29], 1, v[8:9]
	s_and_b64 vcc, exec, s[34:35]
	s_cbranch_vccz .Lcw_nogain_B
	v_add_u32_e32 v30, s26, v16
	v_lshlrev_b32_e32 v30, 2, v30
	v_mov_b32_e32 v31, 0
	v_lshl_add_u64 v[30:31], v[30:31], 0, s[28:29]
	global_load_dword v112, v[30:31], off offset:0
	global_load_dword v113, v[30:31], off offset:32
	global_load_dword v114, v[30:31], off offset:64
	global_load_dword v115, v[30:31], off offset:96
	global_load_dword v116, v[30:31], off offset:128
	global_load_dword v117, v[30:31], off offset:160
	global_load_dword v118, v[30:31], off offset:192
	global_load_dword v119, v[30:31], off offset:224
	s_branch .Lcw_wload_B
.Lcw_nogain_B:
	v_mov_b32_e32 v112, 1.0
	v_mov_b32_e32 v113, 1.0
	v_mov_b32_e32 v114, 1.0
	v_mov_b32_e32 v115, 1.0
	v_mov_b32_e32 v116, 1.0
	v_mov_b32_e32 v117, 1.0
	v_mov_b32_e32 v118, 1.0
	v_mov_b32_e32 v119, 1.0
.Lcw_wload_B:
	global_load_dwordx4 v[80:83], v[10:11], off
	v_lshl_add_u64 v[10:11], v[10:11], 0, s[4:5]
	global_load_dwordx4 v[84:87], v[10:11], off
	v_lshl_add_u64 v[10:11], v[10:11], 0, s[4:5]
	global_load_dwordx4 v[88:91], v[10:11], off
	v_lshl_add_u64 v[10:11], v[10:11], 0, s[4:5]
	global_load_dwordx4 v[92:95], v[10:11], off
	v_lshl_add_u64 v[10:11], v[10:11], 0, s[4:5]
	global_load_dwordx4 v[96:99], v[10:11], off
	v_lshl_add_u64 v[10:11], v[10:11], 0, s[4:5]
	global_load_dwordx4 v[100:103], v[10:11], off
	v_lshl_add_u64 v[10:11], v[10:11], 0, s[4:5]
	global_load_dwordx4 v[104:107], v[10:11], off
	v_lshl_add_u64 v[10:11], v[10:11], 0, s[4:5]
	global_load_dwordx4 v[108:111], v[10:11], off
	s_waitcnt vmcnt(8)
	v_mul_f32_e32 v32, v64, v32
	v_mul_f32_e32 v33, v64, v33
	v_mul_f32_e32 v34, v64, v34
	v_mul_f32_e32 v35, v64, v35
	ds_write_b32 v132, v32 offset:0
	ds_write_b32 v132, v33 offset:4
	ds_write_b32 v132, v34 offset:8
	ds_write_b32 v132, v35 offset:12
	v_mul_f32_e32 v36, v65, v36
	v_mul_f32_e32 v37, v65, v37
	v_mul_f32_e32 v38, v65, v38
	v_mul_f32_e32 v39, v65, v39
	ds_write_b32 v132, v36 offset:1056
	ds_write_b32 v132, v37 offset:1060
	ds_write_b32 v132, v38 offset:1064
	ds_write_b32 v132, v39 offset:1068
	v_mul_f32_e32 v40, v66, v40
	v_mul_f32_e32 v41, v66, v41
	v_mul_f32_e32 v42, v66, v42
	v_mul_f32_e32 v43, v66, v43
	ds_write_b32 v132, v40 offset:2112
	ds_write_b32 v132, v41 offset:2116
	ds_write_b32 v132, v42 offset:2120
	ds_write_b32 v132, v43 offset:2124
	v_mul_f32_e32 v44, v67, v44
	v_mul_f32_e32 v45, v67, v45
	v_mul_f32_e32 v46, v67, v46
	v_mul_f32_e32 v47, v67, v47
	ds_write_b32 v132, v44 offset:3168
	ds_write_b32 v132, v45 offset:3172
	ds_write_b32 v132, v46 offset:3176
	ds_write_b32 v132, v47 offset:3180
	v_mul_f32_e32 v48, v68, v48
	v_mul_f32_e32 v49, v68, v49
	v_mul_f32_e32 v50, v68, v50
	v_mul_f32_e32 v51, v68, v51
	ds_write_b32 v132, v48 offset:4224
	ds_write_b32 v132, v49 offset:4228
	ds_write_b32 v132, v50 offset:4232
	ds_write_b32 v132, v51 offset:4236
	v_mul_f32_e32 v52, v69, v52
	v_mul_f32_e32 v53, v69, v53
	v_mul_f32_e32 v54, v69, v54
	v_mul_f32_e32 v55, v69, v55
	ds_write_b32 v132, v52 offset:5280
	ds_write_b32 v132, v53 offset:5284
	ds_write_b32 v132, v54 offset:5288
	ds_write_b32 v132, v55 offset:5292
	v_mul_f32_e32 v56, v70, v56
	v_mul_f32_e32 v57, v70, v57
	v_mul_f32_e32 v58, v70, v58
	v_mul_f32_e32 v59, v70, v59
	ds_write_b32 v132, v56 offset:6336
	ds_write_b32 v132, v57 offset:6340
	ds_write_b32 v132, v58 offset:6344
	ds_write_b32 v132, v59 offset:6348
	v_mul_f32_e32 v60, v71, v60
	v_mul_f32_e32 v61, v71, v61
	v_mul_f32_e32 v62, v71, v62
	v_mul_f32_e32 v63, v71, v63
	ds_write_b32 v132, v60 offset:7392
	ds_write_b32 v132, v61 offset:7396
	ds_write_b32 v132, v62 offset:7400
	ds_write_b32 v132, v63 offset:7404
	s_waitcnt lgkmcnt(0)
	ds_read2_b32 v[32:33], v17 offset0:0 offset1:33
	ds_read2_b32 v[34:35], v17 offset0:66 offset1:99
	ds_read2_b32 v[36:37], v17 offset0:132 offset1:165
	ds_read2_b32 v[38:39], v17 offset0:198 offset1:231
	ds_read2_b32 v[40:41], v17 offset0:8 offset1:41
	ds_read2_b32 v[42:43], v17 offset0:74 offset1:107
	ds_read2_b32 v[44:45], v17 offset0:140 offset1:173
	ds_read2_b32 v[46:47], v17 offset0:206 offset1:239
	ds_read2_b32 v[48:49], v17 offset0:16 offset1:49
	ds_read2_b32 v[50:51], v17 offset0:82 offset1:115
	ds_read2_b32 v[52:53], v17 offset0:148 offset1:181
	ds_read2_b32 v[54:55], v17 offset0:214 offset1:247
	ds_read2_b32 v[56:57], v17 offset0:24 offset1:57
	ds_read2_b32 v[58:59], v17 offset0:90 offset1:123
	ds_read2_b32 v[60:61], v17 offset0:156 offset1:189
	ds_read2_b32 v[62:63], v17 offset0:222 offset1:255
	s_waitcnt lgkmcnt(12)
	v_cvt_pk_bf16_f32 v32, v32, v33
	v_cvt_pk_bf16_f32 v33, v34, v35
	v_cvt_pk_bf16_f32 v34, v36, v37
	v_cvt_pk_bf16_f32 v35, v38, v39
	global_store_dwordx4 v[72:73], v[32:35], off
	s_waitcnt lgkmcnt(8)
	v_cvt_pk_bf16_f32 v40, v40, v41
	v_cvt_pk_bf16_f32 v41, v42, v43
	v_cvt_pk_bf16_f32 v42, v44, v45
	v_cvt_pk_bf16_f32 v43, v46, v47
	global_store_dwordx4 v[74:75], v[40:43], off
	s_waitcnt lgkmcnt(4)
	v_cvt_pk_bf16_f32 v48, v48, v49
	v_cvt_pk_bf16_f32 v49, v50, v51
	v_cvt_pk_bf16_f32 v50, v52, v53
	v_cvt_pk_bf16_f32 v51, v54, v55
	global_store_dwordx4 v[76:77], v[48:51], off
	s_waitcnt lgkmcnt(0)
	v_cvt_pk_bf16_f32 v56, v56, v57
	v_cvt_pk_bf16_f32 v57, v58, v59
	v_cvt_pk_bf16_f32 v58, v60, v61
	v_cvt_pk_bf16_f32 v59, v62, v63
	global_store_dwordx4 v[78:79], v[56:59], off
	s_mov_b32 s99, 0
	s_branch .LBB0_22
.Lcw_drain:
	s_waitcnt vmcnt(0)
	s_cmp_eq_u32 s98, 0
	s_cbranch_scc1 .Lcw_drain_done
	s_cmp_eq_u32 s99, 0
	s_cbranch_scc1 .Lcw_drainB
	v_mul_f32_e32 v32, v64, v32
	v_mul_f32_e32 v33, v64, v33
	v_mul_f32_e32 v34, v64, v34
	v_mul_f32_e32 v35, v64, v35
	ds_write_b32 v132, v32 offset:0
	ds_write_b32 v132, v33 offset:4
	ds_write_b32 v132, v34 offset:8
	ds_write_b32 v132, v35 offset:12
	v_mul_f32_e32 v36, v65, v36
	v_mul_f32_e32 v37, v65, v37
	v_mul_f32_e32 v38, v65, v38
	v_mul_f32_e32 v39, v65, v39
	ds_write_b32 v132, v36 offset:1056
	ds_write_b32 v132, v37 offset:1060
	ds_write_b32 v132, v38 offset:1064
	ds_write_b32 v132, v39 offset:1068
	v_mul_f32_e32 v40, v66, v40
	v_mul_f32_e32 v41, v66, v41
	v_mul_f32_e32 v42, v66, v42
	v_mul_f32_e32 v43, v66, v43
	ds_write_b32 v132, v40 offset:2112
	ds_write_b32 v132, v41 offset:2116
	ds_write_b32 v132, v42 offset:2120
	ds_write_b32 v132, v43 offset:2124
	v_mul_f32_e32 v44, v67, v44
	v_mul_f32_e32 v45, v67, v45
	v_mul_f32_e32 v46, v67, v46
	v_mul_f32_e32 v47, v67, v47
	ds_write_b32 v132, v44 offset:3168
	ds_write_b32 v132, v45 offset:3172
	ds_write_b32 v132, v46 offset:3176
	ds_write_b32 v132, v47 offset:3180
	v_mul_f32_e32 v48, v68, v48
	v_mul_f32_e32 v49, v68, v49
	v_mul_f32_e32 v50, v68, v50
	v_mul_f32_e32 v51, v68, v51
	ds_write_b32 v132, v48 offset:4224
	ds_write_b32 v132, v49 offset:4228
	ds_write_b32 v132, v50 offset:4232
	ds_write_b32 v132, v51 offset:4236
	v_mul_f32_e32 v52, v69, v52
	v_mul_f32_e32 v53, v69, v53
	v_mul_f32_e32 v54, v69, v54
	v_mul_f32_e32 v55, v69, v55
	ds_write_b32 v132, v52 offset:5280
	ds_write_b32 v132, v53 offset:5284
	ds_write_b32 v132, v54 offset:5288
	ds_write_b32 v132, v55 offset:5292
	v_mul_f32_e32 v56, v70, v56
	v_mul_f32_e32 v57, v70, v57
	v_mul_f32_e32 v58, v70, v58
	v_mul_f32_e32 v59, v70, v59
	ds_write_b32 v132, v56 offset:6336
	ds_write_b32 v132, v57 offset:6340
	ds_write_b32 v132, v58 offset:6344
	ds_write_b32 v132, v59 offset:6348
	v_mul_f32_e32 v60, v71, v60
	v_mul_f32_e32 v61, v71, v61
	v_mul_f32_e32 v62, v71, v62
	v_mul_f32_e32 v63, v71, v63
	ds_write_b32 v132, v60 offset:7392
	ds_write_b32 v132, v61 offset:7396
	ds_write_b32 v132, v62 offset:7400
	ds_write_b32 v132, v63 offset:7404
	s_waitcnt lgkmcnt(0)
	ds_read2_b32 v[32:33], v17 offset0:0 offset1:33
	ds_read2_b32 v[34:35], v17 offset0:66 offset1:99
	ds_read2_b32 v[36:37], v17 offset0:132 offset1:165
	ds_read2_b32 v[38:39], v17 offset0:198 offset1:231
	ds_read2_b32 v[40:41], v17 offset0:8 offset1:41
	ds_read2_b32 v[42:43], v17 offset0:74 offset1:107
	ds_read2_b32 v[44:45], v17 offset0:140 offset1:173
	ds_read2_b32 v[46:47], v17 offset0:206 offset1:239
	ds_read2_b32 v[48:49], v17 offset0:16 offset1:49
	ds_read2_b32 v[50:51], v17 offset0:82 offset1:115
	ds_read2_b32 v[52:53], v17 offset0:148 offset1:181
	ds_read2_b32 v[54:55], v17 offset0:214 offset1:247
	ds_read2_b32 v[56:57], v17 offset0:24 offset1:57
	ds_read2_b32 v[58:59], v17 offset0:90 offset1:123
	ds_read2_b32 v[60:61], v17 offset0:156 offset1:189
	ds_read2_b32 v[62:63], v17 offset0:222 offset1:255
	s_waitcnt lgkmcnt(12)
	v_cvt_pk_bf16_f32 v32, v32, v33
	v_cvt_pk_bf16_f32 v33, v34, v35
	v_cvt_pk_bf16_f32 v34, v36, v37
	v_cvt_pk_bf16_f32 v35, v38, v39
	global_store_dwordx4 v[72:73], v[32:35], off
	s_waitcnt lgkmcnt(8)
	v_cvt_pk_bf16_f32 v40, v40, v41
	v_cvt_pk_bf16_f32 v41, v42, v43
	v_cvt_pk_bf16_f32 v42, v44, v45
	v_cvt_pk_bf16_f32 v43, v46, v47
	global_store_dwordx4 v[74:75], v[40:43], off
	s_waitcnt lgkmcnt(4)
	v_cvt_pk_bf16_f32 v48, v48, v49
	v_cvt_pk_bf16_f32 v49, v50, v51
	v_cvt_pk_bf16_f32 v50, v52, v53
	v_cvt_pk_bf16_f32 v51, v54, v55
	global_store_dwordx4 v[76:77], v[48:51], off
	s_waitcnt lgkmcnt(0)
	v_cvt_pk_bf16_f32 v56, v56, v57
	v_cvt_pk_bf16_f32 v57, v58, v59
	v_cvt_pk_bf16_f32 v58, v60, v61
	v_cvt_pk_bf16_f32 v59, v62, v63
	global_store_dwordx4 v[78:79], v[56:59], off
	s_branch .Lcw_drain_done
.Lcw_drainB:
	v_mul_f32_e32 v80, v112, v80
	v_mul_f32_e32 v81, v112, v81
	v_mul_f32_e32 v82, v112, v82
	v_mul_f32_e32 v83, v112, v83
	ds_write_b32 v132, v80 offset:0
	ds_write_b32 v132, v81 offset:4
	ds_write_b32 v132, v82 offset:8
	ds_write_b32 v132, v83 offset:12
	v_mul_f32_e32 v84, v113, v84
	v_mul_f32_e32 v85, v113, v85
	v_mul_f32_e32 v86, v113, v86
	v_mul_f32_e32 v87, v113, v87
	ds_write_b32 v132, v84 offset:1056
	ds_write_b32 v132, v85 offset:1060
	ds_write_b32 v132, v86 offset:1064
	ds_write_b32 v132, v87 offset:1068
	v_mul_f32_e32 v88, v114, v88
	v_mul_f32_e32 v89, v114, v89
	v_mul_f32_e32 v90, v114, v90
	v_mul_f32_e32 v91, v114, v91
	ds_write_b32 v132, v88 offset:2112
	ds_write_b32 v132, v89 offset:2116
	ds_write_b32 v132, v90 offset:2120
	ds_write_b32 v132, v91 offset:2124
	v_mul_f32_e32 v92, v115, v92
	v_mul_f32_e32 v93, v115, v93
	v_mul_f32_e32 v94, v115, v94
	v_mul_f32_e32 v95, v115, v95
	ds_write_b32 v132, v92 offset:3168
	ds_write_b32 v132, v93 offset:3172
	ds_write_b32 v132, v94 offset:3176
	ds_write_b32 v132, v95 offset:3180
	v_mul_f32_e32 v96, v116, v96
	v_mul_f32_e32 v97, v116, v97
	v_mul_f32_e32 v98, v116, v98
	v_mul_f32_e32 v99, v116, v99
	ds_write_b32 v132, v96 offset:4224
	ds_write_b32 v132, v97 offset:4228
	ds_write_b32 v132, v98 offset:4232
	ds_write_b32 v132, v99 offset:4236
	v_mul_f32_e32 v100, v117, v100
	v_mul_f32_e32 v101, v117, v101
	v_mul_f32_e32 v102, v117, v102
	v_mul_f32_e32 v103, v117, v103
	ds_write_b32 v132, v100 offset:5280
	ds_write_b32 v132, v101 offset:5284
	ds_write_b32 v132, v102 offset:5288
	ds_write_b32 v132, v103 offset:5292
	v_mul_f32_e32 v104, v118, v104
	v_mul_f32_e32 v105, v118, v105
	v_mul_f32_e32 v106, v118, v106
	v_mul_f32_e32 v107, v118, v107
	ds_write_b32 v132, v104 offset:6336
	ds_write_b32 v132, v105 offset:6340
	ds_write_b32 v132, v106 offset:6344
	ds_write_b32 v132, v107 offset:6348
	v_mul_f32_e32 v108, v119, v108
	v_mul_f32_e32 v109, v119, v109
	v_mul_f32_e32 v110, v119, v110
	v_mul_f32_e32 v111, v119, v111
	ds_write_b32 v132, v108 offset:7392
	ds_write_b32 v132, v109 offset:7396
	ds_write_b32 v132, v110 offset:7400
	ds_write_b32 v132, v111 offset:7404
	s_waitcnt lgkmcnt(0)
	ds_read2_b32 v[80:81], v17 offset0:0 offset1:33
	ds_read2_b32 v[82:83], v17 offset0:66 offset1:99
	ds_read2_b32 v[84:85], v17 offset0:132 offset1:165
	ds_read2_b32 v[86:87], v17 offset0:198 offset1:231
	ds_read2_b32 v[88:89], v17 offset0:8 offset1:41
	ds_read2_b32 v[90:91], v17 offset0:74 offset1:107
	ds_read2_b32 v[92:93], v17 offset0:140 offset1:173
	ds_read2_b32 v[94:95], v17 offset0:206 offset1:239
	ds_read2_b32 v[96:97], v17 offset0:16 offset1:49
	ds_read2_b32 v[98:99], v17 offset0:82 offset1:115
	ds_read2_b32 v[100:101], v17 offset0:148 offset1:181
	ds_read2_b32 v[102:103], v17 offset0:214 offset1:247
	ds_read2_b32 v[104:105], v17 offset0:24 offset1:57
	ds_read2_b32 v[106:107], v17 offset0:90 offset1:123
	ds_read2_b32 v[108:109], v17 offset0:156 offset1:189
	ds_read2_b32 v[110:111], v17 offset0:222 offset1:255
	s_waitcnt lgkmcnt(12)
	v_cvt_pk_bf16_f32 v80, v80, v81
	v_cvt_pk_bf16_f32 v81, v82, v83
	v_cvt_pk_bf16_f32 v82, v84, v85
	v_cvt_pk_bf16_f32 v83, v86, v87
	global_store_dwordx4 v[120:121], v[80:83], off
	s_waitcnt lgkmcnt(8)
	v_cvt_pk_bf16_f32 v88, v88, v89
	v_cvt_pk_bf16_f32 v89, v90, v91
	v_cvt_pk_bf16_f32 v90, v92, v93
	v_cvt_pk_bf16_f32 v91, v94, v95
	global_store_dwordx4 v[122:123], v[88:91], off
	s_waitcnt lgkmcnt(4)
	v_cvt_pk_bf16_f32 v96, v96, v97
	v_cvt_pk_bf16_f32 v97, v98, v99
	v_cvt_pk_bf16_f32 v98, v100, v101
	v_cvt_pk_bf16_f32 v99, v102, v103
	global_store_dwordx4 v[124:125], v[96:99], off
	s_waitcnt lgkmcnt(0)
	v_cvt_pk_bf16_f32 v104, v104, v105
	v_cvt_pk_bf16_f32 v105, v106, v107
	v_cvt_pk_bf16_f32 v106, v108, v109
	v_cvt_pk_bf16_f32 v107, v110, v111
	global_store_dwordx4 v[126:127], v[104:107], off
.Lcw_drain_done:
	s_branch .LBB0_104
.LBB0_103:
	s_mov_b32 s42, 64
	s_mov_b64 s[20:21], 64
	v_readlane_b32 s34, v252, 4
	s_cbranch_execz .LBB0_42
	s_branch .LBB0_43
